# nt on the final RMSNorm's output stores and its single-use X / sum-of-squares loads
# speedup vs baseline: 1.0038x; 1.0038x over previous
.LBB0_2312:
	v_lshl_add_u64 v[26:27], s[40:41], 0, v[4:5]
	global_load_dwordx4 v[10:13], v[0:1], off
	global_load_dwordx4 v[14:17], v[0:1], off offset:1024
	global_load_dwordx4 v[18:21], v[0:1], off offset:2048
	flat_load_dwordx4 v[22:25], v[26:27] nt
	v_lshl_add_u64 v[28:29], s[40:41], 0, v[2:3]
	v_add_co_u32_e32 v30, vcc, 0x6600000, v28
	v_add_u32_e32 v8, s10, v8
	s_nop 0
	v_addc_co_u32_e32 v31, vcc, 0, v29, vcc
	flat_load_dwordx2 v[32:33], v[30:31] nt
	flat_load_dwordx2 v[34:35], v[30:31] offset:512 nt
	flat_load_dwordx2 v[36:37], v[30:31] offset:1024 nt
	flat_load_dwordx2 v[38:39], v[30:31] offset:1536 nt
	global_load_dwordx4 v[26:29], v[0:1], off offset:3072
	v_cmp_lt_i32_e32 vcc, s9, v8
	s_or_b64 s[6:7], vcc, s[6:7]
	v_lshl_add_u64 v[2:3], v[2:3], 0, s[0:1]
	v_lshl_add_u64 v[4:5], v[4:5], 0, s[2:3]
	s_waitcnt vmcnt(0) lgkmcnt(0)
	v_mov_b32_e32 v30, v23
	v_mov_b32_e32 v31, v24
	v_mov_b32_e32 v23, v25
	v_pk_add_f32 v[22:23], v[30:31], v[22:23]
	v_lshlrev_b32_e32 v24, 16, v33
	v_add_f32_e32 v42, v22, v23
	v_lshlrev_b32_e32 v22, 16, v32
	v_and_b32_e32 v23, 0xffff0000, v32
	v_add_f32_dpp v42, v42, v42 quad_perm:[1,0,3,2] row_mask:0xf bank_mask:0xf bound_ctrl:1
	v_and_b32_e32 v25, 0xffff0000, v33
	v_lshlrev_b32_e32 v30, 16, v34
	v_add_f32_dpp v42, v42, v42 quad_perm:[2,3,0,1] row_mask:0xf bank_mask:0xf bound_ctrl:1
	v_fmamk_f32 v42, v42, 0x3a800000, v9
	v_mul_f32_e32 v43, 0x4b800000, v42
	v_cmp_gt_f32_e32 vcc, s8, v42
	v_and_b32_e32 v31, 0xffff0000, v34
	v_lshlrev_b32_e32 v32, 16, v35
	v_cndmask_b32_e32 v42, v42, v43, vcc
	v_rsq_f32_e32 v42, v42
	v_and_b32_e32 v33, 0xffff0000, v35
	v_lshlrev_b32_e32 v34, 16, v36
	v_and_b32_e32 v35, 0xffff0000, v36
	v_mul_f32_e32 v43, 0x45800000, v42
	v_cndmask_b32_e32 v42, v42, v43, vcc
	v_lshlrev_b32_e32 v36, 16, v37
	v_and_b32_e32 v37, 0xffff0000, v37
	v_lshlrev_b32_e32 v40, 16, v38
	v_and_b32_e32 v41, 0xffff0000, v38
	v_lshlrev_b32_e32 v38, 16, v39
	v_and_b32_e32 v39, 0xffff0000, v39
	v_pk_mul_f32 v[22:23], v[42:43], v[22:23] op_sel_hi:[0,1]
	v_pk_mul_f32 v[24:25], v[42:43], v[24:25] op_sel_hi:[0,1]
	v_pk_mul_f32 v[30:31], v[42:43], v[30:31] op_sel_hi:[0,1]
	v_pk_mul_f32 v[32:33], v[42:43], v[32:33] op_sel_hi:[0,1]
	v_pk_mul_f32 v[34:35], v[42:43], v[34:35] op_sel_hi:[0,1]
	v_pk_mul_f32 v[36:37], v[42:43], v[36:37] op_sel_hi:[0,1]
	v_pk_mul_f32 v[40:41], v[42:43], v[40:41] op_sel_hi:[0,1]
	v_pk_mul_f32 v[38:39], v[42:43], v[38:39] op_sel_hi:[0,1]
	v_pk_mul_f32 v[12:13], v[12:13], v[24:25]
	v_pk_mul_f32 v[10:11], v[10:11], v[22:23]
	v_pk_mul_f32 v[16:17], v[16:17], v[32:33]
	v_pk_mul_f32 v[14:15], v[14:15], v[30:31]
	v_pk_mul_f32 v[20:21], v[20:21], v[36:37]
	v_pk_mul_f32 v[18:19], v[18:19], v[34:35]
	v_pk_mul_f32 v[24:25], v[28:29], v[38:39]
	v_pk_mul_f32 v[22:23], v[26:27], v[40:41]
	global_store_dwordx4 v[6:7], v[10:13], off offset:-3072 nt
	global_store_dwordx4 v[6:7], v[14:17], off offset:-2048 nt
	global_store_dwordx4 v[6:7], v[18:21], off offset:-1024 nt
	global_store_dwordx4 v[6:7], v[22:25], off nt
	v_lshl_add_u64 v[6:7], v[6:7], 0, s[4:5]
	s_add_i32 s14, s14, 1
	s_cmp_lg_u32 s14, 2
	s_cbranch_scc1 .Lmy_fn_noj
	v_lshl_add_u64 v[2:3], v[2:3], 0, s[16:17]
	v_lshl_add_u64 v[4:5], v[4:5], 0, s[18:19]
	v_lshl_add_u64 v[6:7], v[6:7], 0, s[20:21]
